# diff-attn tile loop rewritten: lockstep 1 barrier per tile, QK of next tile + PV MFMAs interleaved with softmax VALU
# baseline (speedup 1.0000x reference)
.LBB0_757:
	v_mov_b32_e32 v14, v0
	v_mov_b32_e32 v15, v0
	v_mov_b32_e32 v1, v0
	v_mov_b32_e32 v2, v0
	v_mov_b32_e32 v3, v0
	v_mov_b32_e32 v4, v0
	v_mov_b32_e32 v5, v0
	v_mov_b32_e32 v6, v0
	v_mov_b32_e32 v7, v0
	v_mov_b32_e32 v8, v0
	v_mov_b32_e32 v9, v0
	v_mov_b32_e32 v10, v0
	v_mov_b32_e32 v11, v0
	v_mov_b32_e32 v12, v0
	v_mov_b32_e32 v13, v0
	v_mov_b64_e32 v[30:31], v[14:15]
	v_mov_b64_e32 v[46:47], v[14:15]
	v_mov_b64_e32 v[62:63], v[14:15]
	v_mov_b64_e32 v[78:79], v[14:15]
	s_xor_b64 s[0:1], s[0:1], -1
	v_lshl_add_u64 v[188:189], s[14:15], 1, v[180:181]
	s_mov_b32 s25, 0
	v_mov_b32_e32 v187, 0
	v_mov_b32_e32 v208, 0xff800000
	s_mov_b64 s[4:5], 0
	s_mov_b32 s26, s21
	v_mov_b64_e32 v[28:29], v[12:13]
	v_mov_b64_e32 v[26:27], v[10:11]
	v_mov_b64_e32 v[24:25], v[8:9]
	v_mov_b64_e32 v[22:23], v[6:7]
	v_mov_b64_e32 v[20:21], v[4:5]
	v_mov_b64_e32 v[18:19], v[2:3]
	v_mov_b64_e32 v[16:17], v[0:1]
	v_mov_b64_e32 v[44:45], v[12:13]
	v_mov_b64_e32 v[42:43], v[10:11]
	v_mov_b64_e32 v[40:41], v[8:9]
	v_mov_b64_e32 v[38:39], v[6:7]
	v_mov_b64_e32 v[36:37], v[4:5]
	v_mov_b64_e32 v[34:35], v[2:3]
	v_mov_b64_e32 v[32:33], v[0:1]
	v_mov_b64_e32 v[60:61], v[12:13]
	v_mov_b64_e32 v[58:59], v[10:11]
	v_mov_b64_e32 v[56:57], v[8:9]
	v_mov_b64_e32 v[54:55], v[6:7]
	v_mov_b64_e32 v[52:53], v[4:5]
	v_mov_b64_e32 v[50:51], v[2:3]
	v_mov_b64_e32 v[48:49], v[0:1]
	v_mov_b64_e32 v[76:77], v[12:13]
	v_mov_b64_e32 v[74:75], v[10:11]
	v_mov_b64_e32 v[72:73], v[8:9]
	v_mov_b64_e32 v[70:71], v[6:7]
	v_mov_b64_e32 v[68:69], v[4:5]
	v_mov_b64_e32 v[66:67], v[2:3]
	v_mov_b64_e32 v[64:65], v[0:1]
	s_mov_b32 s27, 0
	s_mov_b32 s100, 0
	v_add_u32_e32 v14, v204, v197
	v_add_u32_e32 v15, v204, v198
	ds_read_b128 v[2:5], v14
	ds_read_b128 v[6:9], v14 offset:4096
	ds_read_b128 v[10:13], v209
	ds_read_b128 v[242:245], v15
	ds_read_b128 v[246:249], v15 offset:4096
	ds_read_b128 v[210:213], v209 offset:1024
	v_add_u32_e32 v14, v204, v199
	v_add_u32_e32 v15, v204, v200
	ds_read_b128 v[96:99], v14
	ds_read_b128 v[100:103], v14 offset:4096
	ds_read_b128 v[226:229], v209 offset:2048
	ds_read_b128 v[104:107], v15
	ds_read_b128 v[108:111], v15 offset:4096
	ds_read_b128 v[230:233], v209 offset:3072
	s_waitcnt lgkmcnt(9)
	v_mfma_f32_32x32x16_bf16 v[128:143], v[2:5], v[10:13], 0
	v_mfma_f32_32x32x16_bf16 v[112:127], v[6:9], v[10:13], 0
	s_waitcnt lgkmcnt(6)
	v_mfma_f32_32x32x16_bf16 v[128:143], v[242:245], v[210:213], v[128:143]
	v_mfma_f32_32x32x16_bf16 v[112:127], v[246:249], v[210:213], v[112:127]
	s_waitcnt lgkmcnt(3)
	v_mfma_f32_32x32x16_bf16 v[128:143], v[96:99], v[226:229], v[128:143]
	v_mfma_f32_32x32x16_bf16 v[112:127], v[100:103], v[226:229], v[112:127]
	s_waitcnt lgkmcnt(0)
	v_mfma_f32_32x32x16_bf16 v[128:143], v[104:107], v[230:233], v[128:143]
	v_mfma_f32_32x32x16_bf16 v[112:127], v[108:111], v[230:233], v[112:127]
	s_add_i32 s14, s26, 0xffffff60
	s_cmp_gt_u32 s14, 0xfffffea0
	s_cbranch_scc1 .Ldfp_near_1
	s_sub_i32 s14, s26, 31
	s_cmpk_gt_i32 s14, 0x80
	s_cselect_b32 s14, 0x408, 0
	s_add_i32 s14, s18, s14
	v_mov_b32_e32 v1, s14
	ds_read_b32 v14, v1 offset:29312
	s_nop 7
	s_waitcnt lgkmcnt(0)
	s_nop 3
	v_pk_fma_f32 v[128:129], v[128:129], s[2:3], v[14:15] op_sel_hi:[1,0,0]
	v_pk_fma_f32 v[130:131], v[130:131], s[2:3], v[14:15] op_sel_hi:[1,0,0]
	v_pk_fma_f32 v[132:133], v[132:133], s[2:3], v[14:15] op_sel_hi:[1,0,0]
	v_pk_fma_f32 v[134:135], v[134:135], s[2:3], v[14:15] op_sel_hi:[1,0,0]
	v_pk_fma_f32 v[136:137], v[136:137], s[2:3], v[14:15] op_sel_hi:[1,0,0]
	v_pk_fma_f32 v[138:139], v[138:139], s[2:3], v[14:15] op_sel_hi:[1,0,0]
	v_pk_fma_f32 v[140:141], v[140:141], s[2:3], v[14:15] op_sel_hi:[1,0,0]
	v_pk_fma_f32 v[142:143], v[142:143], s[2:3], v[14:15] op_sel_hi:[1,0,0]
	v_pk_fma_f32 v[112:113], v[112:113], s[2:3], v[14:15] op_sel_hi:[1,0,0]
	v_pk_fma_f32 v[114:115], v[114:115], s[2:3], v[14:15] op_sel_hi:[1,0,0]
	v_pk_fma_f32 v[116:117], v[116:117], s[2:3], v[14:15] op_sel_hi:[1,0,0]
	v_pk_fma_f32 v[118:119], v[118:119], s[2:3], v[14:15] op_sel_hi:[1,0,0]
	v_pk_fma_f32 v[120:121], v[120:121], s[2:3], v[14:15] op_sel_hi:[1,0,0]
	v_pk_fma_f32 v[122:123], v[122:123], s[2:3], v[14:15] op_sel_hi:[1,0,0]
	v_pk_fma_f32 v[124:125], v[124:125], s[2:3], v[14:15] op_sel_hi:[1,0,0]
	v_pk_fma_f32 v[126:127], v[126:127], s[2:3], v[14:15] op_sel_hi:[1,0,0]
	s_branch .Ldfp_biasdone_2
.Ldfp_near_1:
	v_add_u32_e32 v1, s26, v205
	v_lshl_add_u32 v1, v1, 2, s18
	v_add_u32_e32 v1, 0x7280, v1
	s_nop 7
	ds_read2_b32 v[2:3], v1 offset0:0 offset1:1
	ds_read2_b32 v[4:5], v1 offset0:2 offset1:3
	ds_read2_b32 v[6:7], v1 offset0:8 offset1:9
	ds_read2_b32 v[8:9], v1 offset0:10 offset1:11
	ds_read2_b32 v[10:11], v1 offset0:16 offset1:17
	ds_read2_b32 v[12:13], v1 offset0:18 offset1:19
	ds_read2_b32 v[242:243], v1 offset0:24 offset1:25
	ds_read2_b32 v[244:245], v1 offset0:26 offset1:27
	s_waitcnt lgkmcnt(0)
	v_pk_fma_f32 v[128:129], v[128:129], s[2:3], v[2:3] op_sel_hi:[1,0,1]
	v_pk_fma_f32 v[130:131], v[130:131], s[2:3], v[4:5] op_sel_hi:[1,0,1]
	v_pk_fma_f32 v[132:133], v[132:133], s[2:3], v[6:7] op_sel_hi:[1,0,1]
	v_pk_fma_f32 v[134:135], v[134:135], s[2:3], v[8:9] op_sel_hi:[1,0,1]
	v_pk_fma_f32 v[136:137], v[136:137], s[2:3], v[10:11] op_sel_hi:[1,0,1]
	v_pk_fma_f32 v[138:139], v[138:139], s[2:3], v[12:13] op_sel_hi:[1,0,1]
	v_pk_fma_f32 v[140:141], v[140:141], s[2:3], v[242:243] op_sel_hi:[1,0,1]
	v_pk_fma_f32 v[142:143], v[142:143], s[2:3], v[244:245] op_sel_hi:[1,0,1]
	ds_read2_b32 v[2:3], v1 offset0:32 offset1:33
	ds_read2_b32 v[4:5], v1 offset0:34 offset1:35
	ds_read2_b32 v[6:7], v1 offset0:40 offset1:41
	ds_read2_b32 v[8:9], v1 offset0:42 offset1:43
	ds_read2_b32 v[10:11], v1 offset0:48 offset1:49
	ds_read2_b32 v[12:13], v1 offset0:50 offset1:51
	ds_read2_b32 v[242:243], v1 offset0:56 offset1:57
	ds_read2_b32 v[244:245], v1 offset0:58 offset1:59
	s_waitcnt lgkmcnt(0)
	v_pk_fma_f32 v[112:113], v[112:113], s[2:3], v[2:3] op_sel_hi:[1,0,1]
	v_pk_fma_f32 v[114:115], v[114:115], s[2:3], v[4:5] op_sel_hi:[1,0,1]
	v_pk_fma_f32 v[116:117], v[116:117], s[2:3], v[6:7] op_sel_hi:[1,0,1]
	v_pk_fma_f32 v[118:119], v[118:119], s[2:3], v[8:9] op_sel_hi:[1,0,1]
	v_pk_fma_f32 v[120:121], v[120:121], s[2:3], v[10:11] op_sel_hi:[1,0,1]
	v_pk_fma_f32 v[122:123], v[122:123], s[2:3], v[12:13] op_sel_hi:[1,0,1]
	v_pk_fma_f32 v[124:125], v[124:125], s[2:3], v[242:243] op_sel_hi:[1,0,1]
	v_pk_fma_f32 v[126:127], v[126:127], s[2:3], v[244:245] op_sel_hi:[1,0,1]
.Ldfp_biasdone_2:
	v_max3_f32 v225, v128, v129, v130
	v_max3_f32 v225, v225, v131, v132
	v_max3_f32 v225, v225, v133, v134
	v_max3_f32 v225, v225, v135, v136
	v_max3_f32 v225, v225, v137, v138
	v_max3_f32 v225, v225, v139, v140
	v_max3_f32 v225, v225, v141, v142
	v_max3_f32 v225, v225, v143, v112
	v_max3_f32 v225, v225, v113, v114
	v_max3_f32 v225, v225, v115, v116
	v_max3_f32 v225, v225, v117, v118
	v_max3_f32 v225, v225, v119, v120
	v_max3_f32 v225, v225, v121, v122
	v_max3_f32 v225, v225, v123, v124
	v_max3_f32 v225, v225, v125, v126
	v_max_f32_e32 v225, v225, v127
	v_mov_b32_e32 v14, v225
	v_mov_b32_e32 v15, v225
	s_nop 1
	v_permlane32_swap_b32 v14, v15
	s_nop 1
	s_nop 0
	v_max3_f32 v225, v225, v14, v15
	v_add_f32_e32 v14, 0x41000000, v208
	v_cmp_gt_f32_e32 vcc, v225, v14
	s_cbranch_vccz .Ldfp_norescale_3
	v_max_f32_e32 v14, v225, v225
	v_max_f32_e32 v15, v208, v208
	v_max_f32_e32 v14, v15, v14
	v_sub_f32_e32 v15, v208, v14
	v_exp_f32_e32 v15, v15
	v_mov_b32_e32 v208, v14
	s_nop 0
	v_mul_f32_e32 v187, v187, v15
	v_mov_b32_e32 v214, v15
	s_mov_b32 s100, 1
.Ldfp_norescale_3:
	v_pk_add_f32 v[128:129], v[128:129], v[208:209] op_sel_hi:[1,0] neg_lo:[0,1] neg_hi:[0,1]
	v_exp_f32_e32 v128, v128
	v_exp_f32_e32 v129, v129
	v_pk_add_f32 v[130:131], v[130:131], v[208:209] op_sel_hi:[1,0] neg_lo:[0,1] neg_hi:[0,1]
	v_exp_f32_e32 v130, v130
	v_exp_f32_e32 v131, v131
	v_pk_add_f32 v[132:133], v[132:133], v[208:209] op_sel_hi:[1,0] neg_lo:[0,1] neg_hi:[0,1]
	v_exp_f32_e32 v132, v132
	v_exp_f32_e32 v133, v133
	v_pk_add_f32 v[134:135], v[134:135], v[208:209] op_sel_hi:[1,0] neg_lo:[0,1] neg_hi:[0,1]
	v_exp_f32_e32 v134, v134
	v_exp_f32_e32 v135, v135
	v_pk_add_f32 v[136:137], v[136:137], v[208:209] op_sel_hi:[1,0] neg_lo:[0,1] neg_hi:[0,1]
	v_exp_f32_e32 v136, v136
	v_exp_f32_e32 v137, v137
	v_pk_add_f32 v[138:139], v[138:139], v[208:209] op_sel_hi:[1,0] neg_lo:[0,1] neg_hi:[0,1]
	v_exp_f32_e32 v138, v138
	v_exp_f32_e32 v139, v139
	v_pk_add_f32 v[140:141], v[140:141], v[208:209] op_sel_hi:[1,0] neg_lo:[0,1] neg_hi:[0,1]
	v_exp_f32_e32 v140, v140
	v_exp_f32_e32 v141, v141
	v_pk_add_f32 v[142:143], v[142:143], v[208:209] op_sel_hi:[1,0] neg_lo:[0,1] neg_hi:[0,1]
	v_exp_f32_e32 v142, v142
	v_exp_f32_e32 v143, v143
	v_pk_add_f32 v[112:113], v[112:113], v[208:209] op_sel_hi:[1,0] neg_lo:[0,1] neg_hi:[0,1]
	v_exp_f32_e32 v112, v112
	v_exp_f32_e32 v113, v113
	v_pk_add_f32 v[114:115], v[114:115], v[208:209] op_sel_hi:[1,0] neg_lo:[0,1] neg_hi:[0,1]
	v_exp_f32_e32 v114, v114
	v_exp_f32_e32 v115, v115
	v_pk_add_f32 v[116:117], v[116:117], v[208:209] op_sel_hi:[1,0] neg_lo:[0,1] neg_hi:[0,1]
	v_exp_f32_e32 v116, v116
	v_exp_f32_e32 v117, v117
	v_pk_add_f32 v[118:119], v[118:119], v[208:209] op_sel_hi:[1,0] neg_lo:[0,1] neg_hi:[0,1]
	v_exp_f32_e32 v118, v118
	v_exp_f32_e32 v119, v119
	v_pk_add_f32 v[120:121], v[120:121], v[208:209] op_sel_hi:[1,0] neg_lo:[0,1] neg_hi:[0,1]
	v_exp_f32_e32 v120, v120
	v_exp_f32_e32 v121, v121
	v_pk_add_f32 v[122:123], v[122:123], v[208:209] op_sel_hi:[1,0] neg_lo:[0,1] neg_hi:[0,1]
	v_exp_f32_e32 v122, v122
	v_exp_f32_e32 v123, v123
	v_pk_add_f32 v[124:125], v[124:125], v[208:209] op_sel_hi:[1,0] neg_lo:[0,1] neg_hi:[0,1]
	v_exp_f32_e32 v124, v124
	v_exp_f32_e32 v125, v125
	v_pk_add_f32 v[126:127], v[126:127], v[208:209] op_sel_hi:[1,0] neg_lo:[0,1] neg_hi:[0,1]
	v_exp_f32_e32 v126, v126
	v_exp_f32_e32 v127, v127
	s_nop 0
	v_cvt_pk_bf16_f32 v80, v128, v129
	v_cvt_pk_bf16_f32 v81, v130, v131
	v_cvt_pk_bf16_f32 v82, v132, v133
	v_cvt_pk_bf16_f32 v83, v134, v135
	v_cvt_pk_bf16_f32 v84, v136, v137
	v_cvt_pk_bf16_f32 v85, v138, v139
	v_cvt_pk_bf16_f32 v86, v140, v141
	v_cvt_pk_bf16_f32 v87, v142, v143
	v_cvt_pk_bf16_f32 v88, v112, v113
	v_cvt_pk_bf16_f32 v89, v114, v115
	v_cvt_pk_bf16_f32 v90, v116, v117
	v_cvt_pk_bf16_f32 v91, v118, v119
	v_cvt_pk_bf16_f32 v92, v120, v121
	v_cvt_pk_bf16_f32 v93, v122, v123
	v_cvt_pk_bf16_f32 v94, v124, v125
	v_cvt_pk_bf16_f32 v95, v126, v127
	v_pk_add_f32 v[112:113], v[112:113], v[114:115]
	v_pk_add_f32 v[116:117], v[116:117], v[118:119]
	v_pk_add_f32 v[120:121], v[120:121], v[122:123]
	v_pk_add_f32 v[124:125], v[124:125], v[126:127]
	v_pk_add_f32 v[128:129], v[128:129], v[130:131]
	v_pk_add_f32 v[132:133], v[132:133], v[134:135]
	v_pk_add_f32 v[136:137], v[136:137], v[138:139]
	v_pk_add_f32 v[140:141], v[140:141], v[142:143]
	v_pk_add_f32 v[112:113], v[112:113], v[116:117]
	v_pk_add_f32 v[120:121], v[120:121], v[124:125]
	v_pk_add_f32 v[128:129], v[128:129], v[132:133]
	v_pk_add_f32 v[136:137], v[136:137], v[140:141]
	v_pk_add_f32 v[112:113], v[112:113], v[120:121]
	v_pk_add_f32 v[128:129], v[128:129], v[136:137]
	v_pk_add_f32 v[112:113], v[112:113], v[128:129]
	v_add_f32_e32 v112, v112, v113
	v_add_f32_e32 v187, v187, v112
	s_mov_b32 s100, 0
	s_mov_b32 s25, 1
	s_add_i32 s26, s26, 64
.Ldfp_top_4:
	v_lshl_add_u32 v1, s25, 13, v204
	v_add_u32_e32 v14, v1, v197
	v_add_u32_e32 v15, v1, v198
	ds_read_b128 v[2:5], v14
	ds_read_b128 v[6:9], v14 offset:4096
	ds_read_b128 v[10:13], v209
	ds_read_b128 v[242:245], v15
	ds_read_b128 v[246:249], v15 offset:4096
	ds_read_b128 v[210:213], v209 offset:1024
	v_add_u32_e32 v14, v1, v199
	v_add_u32_e32 v15, v1, v200
	ds_read_b128 v[96:99], v14
	ds_read_b128 v[100:103], v14 offset:4096
	ds_read_b128 v[226:229], v209 offset:2048
	ds_read_b128 v[104:107], v15
	ds_read_b128 v[108:111], v15 offset:4096
	ds_read_b128 v[230:233], v209 offset:3072
	s_waitcnt lgkmcnt(9)
	v_mfma_f32_32x32x16_bf16 v[128:143], v[2:5], v[10:13], 0
	v_mfma_f32_32x32x16_bf16 v[112:127], v[6:9], v[10:13], 0
	s_waitcnt lgkmcnt(6)
	v_mfma_f32_32x32x16_bf16 v[128:143], v[242:245], v[210:213], v[128:143]
	v_mfma_f32_32x32x16_bf16 v[112:127], v[246:249], v[210:213], v[112:127]
	s_waitcnt lgkmcnt(3)
	v_mfma_f32_32x32x16_bf16 v[128:143], v[96:99], v[226:229], v[128:143]
	v_mfma_f32_32x32x16_bf16 v[112:127], v[100:103], v[226:229], v[112:127]
	s_waitcnt lgkmcnt(0)
	v_mfma_f32_32x32x16_bf16 v[128:143], v[104:107], v[230:233], v[128:143]
	v_mfma_f32_32x32x16_bf16 v[112:127], v[108:111], v[230:233], v[112:127]
	s_bitcmp1_b32 s27, 0
	s_cselect_b32 s14, 0x5000, 0
	v_add_u32_e32 v250, s14, v201
	s_add_i32 s14, s26, 0xffffff60
	s_cmp_gt_u32 s14, 0xfffffea0
	s_cbranch_scc1 .Ldfp_near_5
	s_sub_i32 s14, s26, 31
	s_cmpk_gt_i32 s14, 0x80
	s_cselect_b32 s14, 0x408, 0
	s_add_i32 s14, s18, s14
	v_mov_b32_e32 v1, s14
	ds_read_b32 v14, v1 offset:29312
	ds_read_b64_tr_b16 v[96:97], v250 offset:24576
	ds_read_b64_tr_b16 v[100:101], v250 offset:24640
	ds_read_b64_tr_b16 v[104:105], v250 offset:24704
	ds_read_b64_tr_b16 v[108:109], v250 offset:24768
	ds_read_b64_tr_b16 v[98:99], v250 offset:27136
	ds_read_b64_tr_b16 v[102:103], v250 offset:27200
	ds_read_b64_tr_b16 v[106:107], v250 offset:27264
	ds_read_b64_tr_b16 v[110:111], v250 offset:27328
	s_waitcnt lgkmcnt(8)
	s_nop 3
	v_pk_fma_f32 v[128:129], v[128:129], s[2:3], v[14:15] op_sel_hi:[1,0,0]
	v_pk_fma_f32 v[130:131], v[130:131], s[2:3], v[14:15] op_sel_hi:[1,0,0]
	v_pk_fma_f32 v[132:133], v[132:133], s[2:3], v[14:15] op_sel_hi:[1,0,0]
	v_pk_fma_f32 v[134:135], v[134:135], s[2:3], v[14:15] op_sel_hi:[1,0,0]
	v_pk_fma_f32 v[136:137], v[136:137], s[2:3], v[14:15] op_sel_hi:[1,0,0]
	v_pk_fma_f32 v[138:139], v[138:139], s[2:3], v[14:15] op_sel_hi:[1,0,0]
	v_pk_fma_f32 v[140:141], v[140:141], s[2:3], v[14:15] op_sel_hi:[1,0,0]
	v_pk_fma_f32 v[142:143], v[142:143], s[2:3], v[14:15] op_sel_hi:[1,0,0]
	v_pk_fma_f32 v[112:113], v[112:113], s[2:3], v[14:15] op_sel_hi:[1,0,0]
	v_pk_fma_f32 v[114:115], v[114:115], s[2:3], v[14:15] op_sel_hi:[1,0,0]
	v_pk_fma_f32 v[116:117], v[116:117], s[2:3], v[14:15] op_sel_hi:[1,0,0]
	v_pk_fma_f32 v[118:119], v[118:119], s[2:3], v[14:15] op_sel_hi:[1,0,0]
	v_pk_fma_f32 v[120:121], v[120:121], s[2:3], v[14:15] op_sel_hi:[1,0,0]
	v_pk_fma_f32 v[122:123], v[122:123], s[2:3], v[14:15] op_sel_hi:[1,0,0]
	v_pk_fma_f32 v[124:125], v[124:125], s[2:3], v[14:15] op_sel_hi:[1,0,0]
	v_pk_fma_f32 v[126:127], v[126:127], s[2:3], v[14:15] op_sel_hi:[1,0,0]
	ds_read_b64_tr_b16 v[226:227], v250 offset:29696
	ds_read_b64_tr_b16 v[230:231], v250 offset:29760
	ds_read_b64_tr_b16 v[234:235], v250 offset:29824
	ds_read_b64_tr_b16 v[238:239], v250 offset:29888
	ds_read_b64_tr_b16 v[228:229], v250 offset:32256
	ds_read_b64_tr_b16 v[232:233], v250 offset:32320
	ds_read_b64_tr_b16 v[236:237], v250 offset:32384
	ds_read_b64_tr_b16 v[240:241], v250 offset:32448
	s_branch .Ldfp_biasdone_6
.Ldfp_near_5:
	v_add_u32_e32 v1, s26, v205
	v_lshl_add_u32 v1, v1, 2, s18
	v_add_u32_e32 v1, 0x7280, v1
	s_nop 7
	ds_read2_b32 v[2:3], v1 offset0:0 offset1:1
	ds_read2_b32 v[4:5], v1 offset0:2 offset1:3
	ds_read2_b32 v[6:7], v1 offset0:8 offset1:9
	ds_read2_b32 v[8:9], v1 offset0:10 offset1:11
	ds_read2_b32 v[10:11], v1 offset0:16 offset1:17
	ds_read2_b32 v[12:13], v1 offset0:18 offset1:19
	ds_read2_b32 v[242:243], v1 offset0:24 offset1:25
	ds_read2_b32 v[244:245], v1 offset0:26 offset1:27
	s_waitcnt lgkmcnt(0)
	v_pk_fma_f32 v[128:129], v[128:129], s[2:3], v[2:3] op_sel_hi:[1,0,1]
	v_pk_fma_f32 v[130:131], v[130:131], s[2:3], v[4:5] op_sel_hi:[1,0,1]
	v_pk_fma_f32 v[132:133], v[132:133], s[2:3], v[6:7] op_sel_hi:[1,0,1]
	v_pk_fma_f32 v[134:135], v[134:135], s[2:3], v[8:9] op_sel_hi:[1,0,1]
	v_pk_fma_f32 v[136:137], v[136:137], s[2:3], v[10:11] op_sel_hi:[1,0,1]
	v_pk_fma_f32 v[138:139], v[138:139], s[2:3], v[12:13] op_sel_hi:[1,0,1]
	v_pk_fma_f32 v[140:141], v[140:141], s[2:3], v[242:243] op_sel_hi:[1,0,1]
	v_pk_fma_f32 v[142:143], v[142:143], s[2:3], v[244:245] op_sel_hi:[1,0,1]
	ds_read2_b32 v[2:3], v1 offset0:32 offset1:33
	ds_read2_b32 v[4:5], v1 offset0:34 offset1:35
	ds_read2_b32 v[6:7], v1 offset0:40 offset1:41
	ds_read2_b32 v[8:9], v1 offset0:42 offset1:43
	ds_read2_b32 v[10:11], v1 offset0:48 offset1:49
	ds_read2_b32 v[12:13], v1 offset0:50 offset1:51
	ds_read2_b32 v[242:243], v1 offset0:56 offset1:57
	ds_read2_b32 v[244:245], v1 offset0:58 offset1:59
	s_waitcnt lgkmcnt(0)
	v_pk_fma_f32 v[112:113], v[112:113], s[2:3], v[2:3] op_sel_hi:[1,0,1]
	v_pk_fma_f32 v[114:115], v[114:115], s[2:3], v[4:5] op_sel_hi:[1,0,1]
	v_pk_fma_f32 v[116:117], v[116:117], s[2:3], v[6:7] op_sel_hi:[1,0,1]
	v_pk_fma_f32 v[118:119], v[118:119], s[2:3], v[8:9] op_sel_hi:[1,0,1]
	v_pk_fma_f32 v[120:121], v[120:121], s[2:3], v[10:11] op_sel_hi:[1,0,1]
	v_pk_fma_f32 v[122:123], v[122:123], s[2:3], v[12:13] op_sel_hi:[1,0,1]
	v_pk_fma_f32 v[124:125], v[124:125], s[2:3], v[242:243] op_sel_hi:[1,0,1]
	v_pk_fma_f32 v[126:127], v[126:127], s[2:3], v[244:245] op_sel_hi:[1,0,1]
	ds_read_b64_tr_b16 v[96:97], v250 offset:24576
	ds_read_b64_tr_b16 v[100:101], v250 offset:24640
	ds_read_b64_tr_b16 v[104:105], v250 offset:24704
	ds_read_b64_tr_b16 v[108:109], v250 offset:24768
	ds_read_b64_tr_b16 v[98:99], v250 offset:27136
	ds_read_b64_tr_b16 v[102:103], v250 offset:27200
	ds_read_b64_tr_b16 v[106:107], v250 offset:27264
	ds_read_b64_tr_b16 v[110:111], v250 offset:27328
	ds_read_b64_tr_b16 v[226:227], v250 offset:29696
	ds_read_b64_tr_b16 v[230:231], v250 offset:29760
	ds_read_b64_tr_b16 v[234:235], v250 offset:29824
	ds_read_b64_tr_b16 v[238:239], v250 offset:29888
	ds_read_b64_tr_b16 v[228:229], v250 offset:32256
	ds_read_b64_tr_b16 v[232:233], v250 offset:32320
	ds_read_b64_tr_b16 v[236:237], v250 offset:32384
	ds_read_b64_tr_b16 v[240:241], v250 offset:32448

.Ldfp_norescale_7:
	v_pk_add_f32 v[128:129], v[128:129], v[208:209] op_sel_hi:[1,0] neg_lo:[0,1] neg_hi:[0,1]
	v_exp_f32_e32 v128, v128
	v_exp_f32_e32 v129, v129
	s_waitcnt lgkmcnt(8)
	v_mfma_f32_32x32x16_bf16 v[64:79], v[96:99], v[80:83], v[64:79]
	v_pk_add_f32 v[130:131], v[130:131], v[208:209] op_sel_hi:[1,0] neg_lo:[0,1] neg_hi:[0,1]
	v_exp_f32_e32 v130, v130
	v_exp_f32_e32 v131, v131
	v_mfma_f32_32x32x16_bf16 v[48:63], v[100:103], v[80:83], v[48:63]
	v_pk_add_f32 v[132:133], v[132:133], v[208:209] op_sel_hi:[1,0] neg_lo:[0,1] neg_hi:[0,1]
	v_exp_f32_e32 v132, v132
	v_exp_f32_e32 v133, v133
	v_mfma_f32_32x32x16_bf16 v[32:47], v[104:107], v[80:83], v[32:47]
	v_pk_add_f32 v[134:135], v[134:135], v[208:209] op_sel_hi:[1,0] neg_lo:[0,1] neg_hi:[0,1]
	v_exp_f32_e32 v134, v134
	v_exp_f32_e32 v135, v135
	v_mfma_f32_32x32x16_bf16 v[16:31], v[108:111], v[80:83], v[16:31]
	ds_read_b64_tr_b16 v[96:97], v250 offset:34816
	ds_read_b64_tr_b16 v[100:101], v250 offset:34880
	ds_read_b64_tr_b16 v[104:105], v250 offset:34944
	ds_read_b64_tr_b16 v[108:109], v250 offset:35008
	ds_read_b64_tr_b16 v[98:99], v250 offset:37376
	ds_read_b64_tr_b16 v[102:103], v250 offset:37440
	ds_read_b64_tr_b16 v[106:107], v250 offset:37504
	ds_read_b64_tr_b16 v[110:111], v250 offset:37568
	v_pk_add_f32 v[136:137], v[136:137], v[208:209] op_sel_hi:[1,0] neg_lo:[0,1] neg_hi:[0,1]
	v_exp_f32_e32 v136, v136
	v_exp_f32_e32 v137, v137
	s_waitcnt lgkmcnt(8)
	v_mfma_f32_32x32x16_bf16 v[64:79], v[226:229], v[84:87], v[64:79]
	v_pk_add_f32 v[138:139], v[138:139], v[208:209] op_sel_hi:[1,0] neg_lo:[0,1] neg_hi:[0,1]
	v_exp_f32_e32 v138, v138
	v_exp_f32_e32 v139, v139
	v_mfma_f32_32x32x16_bf16 v[48:63], v[230:233], v[84:87], v[48:63]
	v_pk_add_f32 v[140:141], v[140:141], v[208:209] op_sel_hi:[1,0] neg_lo:[0,1] neg_hi:[0,1]
	v_exp_f32_e32 v140, v140
	v_exp_f32_e32 v141, v141
	v_mfma_f32_32x32x16_bf16 v[32:47], v[234:237], v[84:87], v[32:47]
	v_pk_add_f32 v[142:143], v[142:143], v[208:209] op_sel_hi:[1,0] neg_lo:[0,1] neg_hi:[0,1]
	v_exp_f32_e32 v142, v142
	v_exp_f32_e32 v143, v143
	v_mfma_f32_32x32x16_bf16 v[16:31], v[238:241], v[84:87], v[16:31]
	ds_read_b64_tr_b16 v[226:227], v250 offset:39936
	ds_read_b64_tr_b16 v[230:231], v250 offset:40000
	ds_read_b64_tr_b16 v[234:235], v250 offset:40064
	ds_read_b64_tr_b16 v[238:239], v250 offset:40128
	ds_read_b64_tr_b16 v[228:229], v250 offset:42496
	ds_read_b64_tr_b16 v[232:233], v250 offset:42560
	ds_read_b64_tr_b16 v[236:237], v250 offset:42624
	ds_read_b64_tr_b16 v[240:241], v250 offset:42688
	v_pk_add_f32 v[112:113], v[112:113], v[208:209] op_sel_hi:[1,0] neg_lo:[0,1] neg_hi:[0,1]
	v_exp_f32_e32 v112, v112
	v_exp_f32_e32 v113, v113
	s_waitcnt lgkmcnt(8)
	v_mfma_f32_32x32x16_bf16 v[64:79], v[96:99], v[88:91], v[64:79]
	v_pk_add_f32 v[114:115], v[114:115], v[208:209] op_sel_hi:[1,0] neg_lo:[0,1] neg_hi:[0,1]
	v_exp_f32_e32 v114, v114
	v_exp_f32_e32 v115, v115
	v_mfma_f32_32x32x16_bf16 v[48:63], v[100:103], v[88:91], v[48:63]
	v_pk_add_f32 v[116:117], v[116:117], v[208:209] op_sel_hi:[1,0] neg_lo:[0,1] neg_hi:[0,1]
	v_exp_f32_e32 v116, v116
	v_exp_f32_e32 v117, v117
	v_mfma_f32_32x32x16_bf16 v[32:47], v[104:107], v[88:91], v[32:47]
	v_pk_add_f32 v[118:119], v[118:119], v[208:209] op_sel_hi:[1,0] neg_lo:[0,1] neg_hi:[0,1]
	v_exp_f32_e32 v118, v118
	v_exp_f32_e32 v119, v119
	v_mfma_f32_32x32x16_bf16 v[16:31], v[108:111], v[88:91], v[16:31]
	v_pk_add_f32 v[120:121], v[120:121], v[208:209] op_sel_hi:[1,0] neg_lo:[0,1] neg_hi:[0,1]
	v_exp_f32_e32 v120, v120
	v_exp_f32_e32 v121, v121
	s_waitcnt lgkmcnt(0)
	v_mfma_f32_32x32x16_bf16 v[64:79], v[226:229], v[92:95], v[64:79]
	v_pk_add_f32 v[122:123], v[122:123], v[208:209] op_sel_hi:[1,0] neg_lo:[0,1] neg_hi:[0,1]
	v_exp_f32_e32 v122, v122
	v_exp_f32_e32 v123, v123
	v_mfma_f32_32x32x16_bf16 v[48:63], v[230:233], v[92:95], v[48:63]
	v_pk_add_f32 v[124:125], v[124:125], v[208:209] op_sel_hi:[1,0] neg_lo:[0,1] neg_hi:[0,1]
	v_exp_f32_e32 v124, v124
	v_exp_f32_e32 v125, v125
	v_mfma_f32_32x32x16_bf16 v[32:47], v[234:237], v[92:95], v[32:47]
	v_pk_add_f32 v[126:127], v[126:127], v[208:209] op_sel_hi:[1,0] neg_lo:[0,1] neg_hi:[0,1]
	v_exp_f32_e32 v126, v126
	v_exp_f32_e32 v127, v127
	v_mfma_f32_32x32x16_bf16 v[16:31], v[238:241], v[92:95], v[16:31]
	s_nop 0
	v_cvt_pk_bf16_f32 v80, v128, v129
	v_cvt_pk_bf16_f32 v81, v130, v131
	v_cvt_pk_bf16_f32 v82, v132, v133
	v_cvt_pk_bf16_f32 v83, v134, v135
	v_cvt_pk_bf16_f32 v84, v136, v137
	v_cvt_pk_bf16_f32 v85, v138, v139
	v_cvt_pk_bf16_f32 v86, v140, v141
	v_cvt_pk_bf16_f32 v87, v142, v143
	v_cvt_pk_bf16_f32 v88, v112, v113
	v_cvt_pk_bf16_f32 v89, v114, v115
	v_cvt_pk_bf16_f32 v90, v116, v117
	v_cvt_pk_bf16_f32 v91, v118, v119
	v_cvt_pk_bf16_f32 v92, v120, v121
	v_cvt_pk_bf16_f32 v93, v122, v123
	v_cvt_pk_bf16_f32 v94, v124, v125
	v_cvt_pk_bf16_f32 v95, v126, v127
	v_pk_add_f32 v[112:113], v[112:113], v[114:115]
	v_pk_add_f32 v[116:117], v[116:117], v[118:119]
	v_pk_add_f32 v[120:121], v[120:121], v[122:123]
	v_pk_add_f32 v[124:125], v[124:125], v[126:127]
	v_pk_add_f32 v[128:129], v[128:129], v[130:131]
	v_pk_add_f32 v[132:133], v[132:133], v[134:135]
	v_pk_add_f32 v[136:137], v[136:137], v[138:139]
	v_pk_add_f32 v[140:141], v[140:141], v[142:143]
	v_pk_add_f32 v[112:113], v[112:113], v[116:117]
	v_pk_add_f32 v[120:121], v[120:121], v[124:125]
	v_pk_add_f32 v[128:129], v[128:129], v[132:133]
	v_pk_add_f32 v[136:137], v[136:137], v[140:141]
	v_pk_add_f32 v[112:113], v[112:113], v[120:121]
	v_pk_add_f32 v[128:129], v[128:129], v[136:137]
	v_pk_add_f32 v[112:113], v[112:113], v[128:129]
	v_add_f32_e32 v112, v112, v113
	v_add_f32_e32 v187, v187, v112
	s_add_i32 s14, s27, 1
	s_bitcmp1_b32 s14, 0
	s_cselect_b32 s15, 0x5000, 0
	s_add_i32 s14, s25, 1
	s_cmp_lg_u32 s25, 2
	s_cselect_b32 s14, s14, 0
	v_lshl_add_u32 v251, s14, 13, v192
	s_waitcnt vmcnt(2)
	ds_write_b128 v251, v[156:159]
	v_add3_u32 v251, s15, v193, v194
	s_waitcnt vmcnt(1)
	ds_write_b128 v251, v[148:151] offset:24576
	v_add3_u32 v251, s15, v195, v196
	s_waitcnt vmcnt(0)
	ds_write_b128 v251, v[152:155] offset:24576
	s_cmp_gt_u32 s27, 28
	s_cbranch_scc1 .Ldfp_skipk_8
	v_lshl_add_u64 v[14:15], v[188:189], 0, s[4:5]
	global_load_dwordx4 v[156:159], v[14:15], off
.Ldfp_skipk_8:
	v_lshl_add_u64 v[14:15], v[184:185], 0, s[4:5]
	global_load_dwordx4 v[148:151], v[14:15], off
	v_lshl_add_u64 v[14:15], v[182:183], 0, s[4:5]
	global_load_dwordx4 v[152:155], v[14:15], off
	s_cmp_eq_u32 s100, 0
	s_cbranch_scc1 .Ldfp_noapply_9
	s_nop 7
	s_nop 7
	v_pk_mul_f32 v[78:79], v[78:79], v[214:215] op_sel_hi:[1,0]
	v_pk_mul_f32 v[76:77], v[76:77], v[214:215] op_sel_hi:[1,0]
	v_pk_mul_f32 v[74:75], v[74:75], v[214:215] op_sel_hi:[1,0]
	v_pk_mul_f32 v[72:73], v[72:73], v[214:215] op_sel_hi:[1,0]
	v_pk_mul_f32 v[70:71], v[70:71], v[214:215] op_sel_hi:[1,0]
	v_pk_mul_f32 v[68:69], v[68:69], v[214:215] op_sel_hi:[1,0]
	v_pk_mul_f32 v[66:67], v[66:67], v[214:215] op_sel_hi:[1,0]
	v_pk_mul_f32 v[64:65], v[64:65], v[214:215] op_sel_hi:[1,0]
	v_pk_mul_f32 v[62:63], v[62:63], v[214:215] op_sel_hi:[1,0]
	v_pk_mul_f32 v[60:61], v[60:61], v[214:215] op_sel_hi:[1,0]
	v_pk_mul_f32 v[58:59], v[58:59], v[214:215] op_sel_hi:[1,0]
	v_pk_mul_f32 v[56:57], v[56:57], v[214:215] op_sel_hi:[1,0]
	v_pk_mul_f32 v[54:55], v[54:55], v[214:215] op_sel_hi:[1,0]
	v_pk_mul_f32 v[52:53], v[52:53], v[214:215] op_sel_hi:[1,0]
	v_pk_mul_f32 v[50:51], v[50:51], v[214:215] op_sel_hi:[1,0]
	v_pk_mul_f32 v[48:49], v[48:49], v[214:215] op_sel_hi:[1,0]
	v_pk_mul_f32 v[46:47], v[46:47], v[214:215] op_sel_hi:[1,0]
	v_pk_mul_f32 v[44:45], v[44:45], v[214:215] op_sel_hi:[1,0]
	v_pk_mul_f32 v[42:43], v[42:43], v[214:215] op_sel_hi:[1,0]
	v_pk_mul_f32 v[40:41], v[40:41], v[214:215] op_sel_hi:[1,0]
	v_pk_mul_f32 v[38:39], v[38:39], v[214:215] op_sel_hi:[1,0]
	v_pk_mul_f32 v[36:37], v[36:37], v[214:215] op_sel_hi:[1,0]
	v_pk_mul_f32 v[34:35], v[34:35], v[214:215] op_sel_hi:[1,0]
	v_pk_mul_f32 v[32:33], v[32:33], v[214:215] op_sel_hi:[1,0]
	v_pk_mul_f32 v[30:31], v[30:31], v[214:215] op_sel_hi:[1,0]
	v_pk_mul_f32 v[28:29], v[28:29], v[214:215] op_sel_hi:[1,0]
	v_pk_mul_f32 v[26:27], v[26:27], v[214:215] op_sel_hi:[1,0]
	v_pk_mul_f32 v[24:25], v[24:25], v[214:215] op_sel_hi:[1,0]
	v_pk_mul_f32 v[22:23], v[22:23], v[214:215] op_sel_hi:[1,0]
	v_pk_mul_f32 v[20:21], v[20:21], v[214:215] op_sel_hi:[1,0]
	v_pk_mul_f32 v[18:19], v[18:19], v[214:215] op_sel_hi:[1,0]
	v_pk_mul_f32 v[16:17], v[16:17], v[214:215] op_sel_hi:[1,0]
	s_mov_b32 s100, 0
.Ldfp_noapply_9:
	s_waitcnt lgkmcnt(0)
	s_barrier
	s_add_i32 s14, s25, 1
	s_cmp_lg_u32 s25, 2
	s_cselect_b32 s25, s14, 0
	s_add_u32 s4, s4, 0x180000
	s_addc_u32 s5, s5, 0
	s_add_i32 s26, s26, 64
	s_add_i32 s27, s27, 1
	s_cmp_lt_u32 s27, 30
	s_cbranch_scc1 .Ldfp_top_4
	v_lshl_add_u32 v1, s25, 13, v204
	v_add_u32_e32 v14, v1, v197
	v_add_u32_e32 v15, v1, v198
	ds_read_b128 v[2:5], v14
	ds_read_b128 v[6:9], v14 offset:4096
	ds_read_b128 v[10:13], v209
	ds_read_b128 v[242:245], v15
	ds_read_b128 v[246:249], v15 offset:4096
	ds_read_b128 v[210:213], v209 offset:1024
	v_add_u32_e32 v14, v1, v199
	v_add_u32_e32 v15, v1, v200
	ds_read_b128 v[96:99], v14
	ds_read_b128 v[100:103], v14 offset:4096
	ds_read_b128 v[226:229], v209 offset:2048
	ds_read_b128 v[104:107], v15
	ds_read_b128 v[108:111], v15 offset:4096
	ds_read_b128 v[230:233], v209 offset:3072
	s_waitcnt lgkmcnt(9)
	v_mfma_f32_32x32x16_bf16 v[128:143], v[2:5], v[10:13], 0
	v_mfma_f32_32x32x16_bf16 v[112:127], v[6:9], v[10:13], 0
	s_waitcnt lgkmcnt(6)
	v_mfma_f32_32x32x16_bf16 v[128:143], v[242:245], v[210:213], v[128:143]
	v_mfma_f32_32x32x16_bf16 v[112:127], v[246:249], v[210:213], v[112:127]
	s_waitcnt lgkmcnt(3)
	v_mfma_f32_32x32x16_bf16 v[128:143], v[96:99], v[226:229], v[128:143]
	v_mfma_f32_32x32x16_bf16 v[112:127], v[100:103], v[226:229], v[112:127]
	s_waitcnt lgkmcnt(0)
	v_mfma_f32_32x32x16_bf16 v[128:143], v[104:107], v[230:233], v[128:143]
	v_mfma_f32_32x32x16_bf16 v[112:127], v[108:111], v[230:233], v[112:127]
	s_bitcmp1_b32 s27, 0
	s_cselect_b32 s14, 0x5000, 0
	v_add_u32_e32 v250, s14, v201
	s_add_i32 s14, s26, 0xffffff60
	s_cmp_gt_u32 s14, 0xfffffea0
	s_cbranch_scc1 .Ldfp_near_10
	s_sub_i32 s14, s26, 31
	s_cmpk_gt_i32 s14, 0x80
	s_cselect_b32 s14, 0x408, 0
	s_add_i32 s14, s18, s14
	v_mov_b32_e32 v1, s14
	ds_read_b32 v14, v1 offset:29312
	ds_read_b64_tr_b16 v[96:97], v250 offset:24576
	ds_read_b64_tr_b16 v[100:101], v250 offset:24640
	ds_read_b64_tr_b16 v[104:105], v250 offset:24704
	ds_read_b64_tr_b16 v[108:109], v250 offset:24768
	ds_read_b64_tr_b16 v[98:99], v250 offset:27136
	ds_read_b64_tr_b16 v[102:103], v250 offset:27200
	ds_read_b64_tr_b16 v[106:107], v250 offset:27264
	ds_read_b64_tr_b16 v[110:111], v250 offset:27328
	s_waitcnt lgkmcnt(8)
	s_nop 3
	v_pk_fma_f32 v[128:129], v[128:129], s[2:3], v[14:15] op_sel_hi:[1,0,0]
	v_pk_fma_f32 v[130:131], v[130:131], s[2:3], v[14:15] op_sel_hi:[1,0,0]
	v_pk_fma_f32 v[132:133], v[132:133], s[2:3], v[14:15] op_sel_hi:[1,0,0]
	v_pk_fma_f32 v[134:135], v[134:135], s[2:3], v[14:15] op_sel_hi:[1,0,0]
	v_pk_fma_f32 v[136:137], v[136:137], s[2:3], v[14:15] op_sel_hi:[1,0,0]
	v_pk_fma_f32 v[138:139], v[138:139], s[2:3], v[14:15] op_sel_hi:[1,0,0]
	v_pk_fma_f32 v[140:141], v[140:141], s[2:3], v[14:15] op_sel_hi:[1,0,0]
	v_pk_fma_f32 v[142:143], v[142:143], s[2:3], v[14:15] op_sel_hi:[1,0,0]
	v_pk_fma_f32 v[112:113], v[112:113], s[2:3], v[14:15] op_sel_hi:[1,0,0]
	v_pk_fma_f32 v[114:115], v[114:115], s[2:3], v[14:15] op_sel_hi:[1,0,0]
	v_pk_fma_f32 v[116:117], v[116:117], s[2:3], v[14:15] op_sel_hi:[1,0,0]
	v_pk_fma_f32 v[118:119], v[118:119], s[2:3], v[14:15] op_sel_hi:[1,0,0]
	v_pk_fma_f32 v[120:121], v[120:121], s[2:3], v[14:15] op_sel_hi:[1,0,0]
	v_pk_fma_f32 v[122:123], v[122:123], s[2:3], v[14:15] op_sel_hi:[1,0,0]
	v_pk_fma_f32 v[124:125], v[124:125], s[2:3], v[14:15] op_sel_hi:[1,0,0]
	v_pk_fma_f32 v[126:127], v[126:127], s[2:3], v[14:15] op_sel_hi:[1,0,0]
	ds_read_b64_tr_b16 v[226:227], v250 offset:29696
	ds_read_b64_tr_b16 v[230:231], v250 offset:29760
	ds_read_b64_tr_b16 v[234:235], v250 offset:29824
	ds_read_b64_tr_b16 v[238:239], v250 offset:29888
	ds_read_b64_tr_b16 v[228:229], v250 offset:32256
	ds_read_b64_tr_b16 v[232:233], v250 offset:32320
	ds_read_b64_tr_b16 v[236:237], v250 offset:32384
	ds_read_b64_tr_b16 v[240:241], v250 offset:32448
	s_branch .Ldfp_biasdone_11

.Ldfp_norescale_12:
	v_pk_add_f32 v[128:129], v[128:129], v[208:209] op_sel_hi:[1,0] neg_lo:[0,1] neg_hi:[0,1]
	v_exp_f32_e32 v128, v128
	v_exp_f32_e32 v129, v129
	s_waitcnt lgkmcnt(8)
	v_mfma_f32_32x32x16_bf16 v[64:79], v[96:99], v[80:83], v[64:79]
	v_pk_add_f32 v[130:131], v[130:131], v[208:209] op_sel_hi:[1,0] neg_lo:[0,1] neg_hi:[0,1]
	v_exp_f32_e32 v130, v130
	v_exp_f32_e32 v131, v131
	v_mfma_f32_32x32x16_bf16 v[48:63], v[100:103], v[80:83], v[48:63]
	v_pk_add_f32 v[132:133], v[132:133], v[208:209] op_sel_hi:[1,0] neg_lo:[0,1] neg_hi:[0,1]
	v_exp_f32_e32 v132, v132
	v_exp_f32_e32 v133, v133
	v_mfma_f32_32x32x16_bf16 v[32:47], v[104:107], v[80:83], v[32:47]
	v_pk_add_f32 v[134:135], v[134:135], v[208:209] op_sel_hi:[1,0] neg_lo:[0,1] neg_hi:[0,1]
	v_exp_f32_e32 v134, v134
	v_exp_f32_e32 v135, v135
	v_mfma_f32_32x32x16_bf16 v[16:31], v[108:111], v[80:83], v[16:31]
	ds_read_b64_tr_b16 v[96:97], v250 offset:34816
	ds_read_b64_tr_b16 v[100:101], v250 offset:34880
	ds_read_b64_tr_b16 v[104:105], v250 offset:34944
	ds_read_b64_tr_b16 v[108:109], v250 offset:35008
	ds_read_b64_tr_b16 v[98:99], v250 offset:37376
	ds_read_b64_tr_b16 v[102:103], v250 offset:37440
	ds_read_b64_tr_b16 v[106:107], v250 offset:37504
	ds_read_b64_tr_b16 v[110:111], v250 offset:37568
	v_pk_add_f32 v[136:137], v[136:137], v[208:209] op_sel_hi:[1,0] neg_lo:[0,1] neg_hi:[0,1]
	v_exp_f32_e32 v136, v136
	v_exp_f32_e32 v137, v137
	s_waitcnt lgkmcnt(8)
	v_mfma_f32_32x32x16_bf16 v[64:79], v[226:229], v[84:87], v[64:79]
	v_pk_add_f32 v[138:139], v[138:139], v[208:209] op_sel_hi:[1,0] neg_lo:[0,1] neg_hi:[0,1]
	v_exp_f32_e32 v138, v138
	v_exp_f32_e32 v139, v139
	v_mfma_f32_32x32x16_bf16 v[48:63], v[230:233], v[84:87], v[48:63]
	v_pk_add_f32 v[140:141], v[140:141], v[208:209] op_sel_hi:[1,0] neg_lo:[0,1] neg_hi:[0,1]
	v_exp_f32_e32 v140, v140
	v_exp_f32_e32 v141, v141
	v_mfma_f32_32x32x16_bf16 v[32:47], v[234:237], v[84:87], v[32:47]
	v_pk_add_f32 v[142:143], v[142:143], v[208:209] op_sel_hi:[1,0] neg_lo:[0,1] neg_hi:[0,1]
	v_exp_f32_e32 v142, v142
	v_exp_f32_e32 v143, v143
	v_mfma_f32_32x32x16_bf16 v[16:31], v[238:241], v[84:87], v[16:31]
	ds_read_b64_tr_b16 v[226:227], v250 offset:39936
	ds_read_b64_tr_b16 v[230:231], v250 offset:40000
	ds_read_b64_tr_b16 v[234:235], v250 offset:40064
	ds_read_b64_tr_b16 v[238:239], v250 offset:40128
	ds_read_b64_tr_b16 v[228:229], v250 offset:42496
	ds_read_b64_tr_b16 v[232:233], v250 offset:42560
	ds_read_b64_tr_b16 v[236:237], v250 offset:42624
	ds_read_b64_tr_b16 v[240:241], v250 offset:42688
	v_pk_add_f32 v[112:113], v[112:113], v[208:209] op_sel_hi:[1,0] neg_lo:[0,1] neg_hi:[0,1]
	v_exp_f32_e32 v112, v112
	v_exp_f32_e32 v113, v113
	s_waitcnt lgkmcnt(8)
	v_mfma_f32_32x32x16_bf16 v[64:79], v[96:99], v[88:91], v[64:79]
	v_pk_add_f32 v[114:115], v[114:115], v[208:209] op_sel_hi:[1,0] neg_lo:[0,1] neg_hi:[0,1]
	v_exp_f32_e32 v114, v114
	v_exp_f32_e32 v115, v115
	v_mfma_f32_32x32x16_bf16 v[48:63], v[100:103], v[88:91], v[48:63]
	v_pk_add_f32 v[116:117], v[116:117], v[208:209] op_sel_hi:[1,0] neg_lo:[0,1] neg_hi:[0,1]
	v_exp_f32_e32 v116, v116
	v_exp_f32_e32 v117, v117
	v_mfma_f32_32x32x16_bf16 v[32:47], v[104:107], v[88:91], v[32:47]
	v_pk_add_f32 v[118:119], v[118:119], v[208:209] op_sel_hi:[1,0] neg_lo:[0,1] neg_hi:[0,1]
	v_exp_f32_e32 v118, v118
	v_exp_f32_e32 v119, v119
	v_mfma_f32_32x32x16_bf16 v[16:31], v[108:111], v[88:91], v[16:31]
	v_pk_add_f32 v[120:121], v[120:121], v[208:209] op_sel_hi:[1,0] neg_lo:[0,1] neg_hi:[0,1]
	v_exp_f32_e32 v120, v120
	v_exp_f32_e32 v121, v121
	s_waitcnt lgkmcnt(0)
	v_mfma_f32_32x32x16_bf16 v[64:79], v[226:229], v[92:95], v[64:79]
	v_pk_add_f32 v[122:123], v[122:123], v[208:209] op_sel_hi:[1,0] neg_lo:[0,1] neg_hi:[0,1]
	v_exp_f32_e32 v122, v122
	v_exp_f32_e32 v123, v123
	v_mfma_f32_32x32x16_bf16 v[48:63], v[230:233], v[92:95], v[48:63]
	v_pk_add_f32 v[124:125], v[124:125], v[208:209] op_sel_hi:[1,0] neg_lo:[0,1] neg_hi:[0,1]
	v_exp_f32_e32 v124, v124
	v_exp_f32_e32 v125, v125
	v_mfma_f32_32x32x16_bf16 v[32:47], v[234:237], v[92:95], v[32:47]
	v_pk_add_f32 v[126:127], v[126:127], v[208:209] op_sel_hi:[1,0] neg_lo:[0,1] neg_hi:[0,1]
	v_exp_f32_e32 v126, v126
	v_exp_f32_e32 v127, v127
	v_mfma_f32_32x32x16_bf16 v[16:31], v[238:241], v[92:95], v[16:31]
	s_nop 0
	v_cvt_pk_bf16_f32 v80, v128, v129
	v_cvt_pk_bf16_f32 v81, v130, v131
	v_cvt_pk_bf16_f32 v82, v132, v133
	v_cvt_pk_bf16_f32 v83, v134, v135
	v_cvt_pk_bf16_f32 v84, v136, v137
	v_cvt_pk_bf16_f32 v85, v138, v139
	v_cvt_pk_bf16_f32 v86, v140, v141
	v_cvt_pk_bf16_f32 v87, v142, v143
	v_cvt_pk_bf16_f32 v88, v112, v113
	v_cvt_pk_bf16_f32 v89, v114, v115
	v_cvt_pk_bf16_f32 v90, v116, v117
	v_cvt_pk_bf16_f32 v91, v118, v119
	v_cvt_pk_bf16_f32 v92, v120, v121
	v_cvt_pk_bf16_f32 v93, v122, v123
	v_cvt_pk_bf16_f32 v94, v124, v125
	v_cvt_pk_bf16_f32 v95, v126, v127
	v_pk_add_f32 v[112:113], v[112:113], v[114:115]
	v_pk_add_f32 v[116:117], v[116:117], v[118:119]
	v_pk_add_f32 v[120:121], v[120:121], v[122:123]
	v_pk_add_f32 v[124:125], v[124:125], v[126:127]
	v_pk_add_f32 v[128:129], v[128:129], v[130:131]
	v_pk_add_f32 v[132:133], v[132:133], v[134:135]
	v_pk_add_f32 v[136:137], v[136:137], v[138:139]
	v_pk_add_f32 v[140:141], v[140:141], v[142:143]
	v_pk_add_f32 v[112:113], v[112:113], v[116:117]
	v_pk_add_f32 v[120:121], v[120:121], v[124:125]
	v_pk_add_f32 v[128:129], v[128:129], v[132:133]
	v_pk_add_f32 v[136:137], v[136:137], v[140:141]
	v_pk_add_f32 v[112:113], v[112:113], v[120:121]
	v_pk_add_f32 v[128:129], v[128:129], v[136:137]
	v_pk_add_f32 v[112:113], v[112:113], v[128:129]
	v_add_f32_e32 v112, v112, v113
	v_add_f32_e32 v187, v187, v112
	s_add_i32 s14, s27, 1
	s_bitcmp1_b32 s14, 0
	s_cselect_b32 s15, 0x5000, 0
	v_add3_u32 v251, s15, v193, v194
	s_waitcnt vmcnt(1)
	ds_write_b128 v251, v[148:151] offset:24576
	v_add3_u32 v251, s15, v195, v196
	s_waitcnt vmcnt(0)
	ds_write_b128 v251, v[152:155] offset:24576
	s_cmp_eq_u32 s100, 0
	s_cbranch_scc1 .Ldfp_noapply_13
	s_nop 7
	s_nop 7
	v_pk_mul_f32 v[78:79], v[78:79], v[214:215] op_sel_hi:[1,0]
	v_pk_mul_f32 v[76:77], v[76:77], v[214:215] op_sel_hi:[1,0]
	v_pk_mul_f32 v[74:75], v[74:75], v[214:215] op_sel_hi:[1,0]
	v_pk_mul_f32 v[72:73], v[72:73], v[214:215] op_sel_hi:[1,0]
	v_pk_mul_f32 v[70:71], v[70:71], v[214:215] op_sel_hi:[1,0]
	v_pk_mul_f32 v[68:69], v[68:69], v[214:215] op_sel_hi:[1,0]
	v_pk_mul_f32 v[66:67], v[66:67], v[214:215] op_sel_hi:[1,0]
	v_pk_mul_f32 v[64:65], v[64:65], v[214:215] op_sel_hi:[1,0]
	v_pk_mul_f32 v[62:63], v[62:63], v[214:215] op_sel_hi:[1,0]
	v_pk_mul_f32 v[60:61], v[60:61], v[214:215] op_sel_hi:[1,0]
	v_pk_mul_f32 v[58:59], v[58:59], v[214:215] op_sel_hi:[1,0]
	v_pk_mul_f32 v[56:57], v[56:57], v[214:215] op_sel_hi:[1,0]
	v_pk_mul_f32 v[54:55], v[54:55], v[214:215] op_sel_hi:[1,0]
	v_pk_mul_f32 v[52:53], v[52:53], v[214:215] op_sel_hi:[1,0]
	v_pk_mul_f32 v[50:51], v[50:51], v[214:215] op_sel_hi:[1,0]
	v_pk_mul_f32 v[48:49], v[48:49], v[214:215] op_sel_hi:[1,0]
	v_pk_mul_f32 v[46:47], v[46:47], v[214:215] op_sel_hi:[1,0]
	v_pk_mul_f32 v[44:45], v[44:45], v[214:215] op_sel_hi:[1,0]
	v_pk_mul_f32 v[42:43], v[42:43], v[214:215] op_sel_hi:[1,0]
	v_pk_mul_f32 v[40:41], v[40:41], v[214:215] op_sel_hi:[1,0]
	v_pk_mul_f32 v[38:39], v[38:39], v[214:215] op_sel_hi:[1,0]
	v_pk_mul_f32 v[36:37], v[36:37], v[214:215] op_sel_hi:[1,0]
	v_pk_mul_f32 v[34:35], v[34:35], v[214:215] op_sel_hi:[1,0]
	v_pk_mul_f32 v[32:33], v[32:33], v[214:215] op_sel_hi:[1,0]
	v_pk_mul_f32 v[30:31], v[30:31], v[214:215] op_sel_hi:[1,0]
	v_pk_mul_f32 v[28:29], v[28:29], v[214:215] op_sel_hi:[1,0]
	v_pk_mul_f32 v[26:27], v[26:27], v[214:215] op_sel_hi:[1,0]
	v_pk_mul_f32 v[24:25], v[24:25], v[214:215] op_sel_hi:[1,0]
	v_pk_mul_f32 v[22:23], v[22:23], v[214:215] op_sel_hi:[1,0]
	v_pk_mul_f32 v[20:21], v[20:21], v[214:215] op_sel_hi:[1,0]
	v_pk_mul_f32 v[18:19], v[18:19], v[214:215] op_sel_hi:[1,0]
	v_pk_mul_f32 v[16:17], v[16:17], v[214:215] op_sel_hi:[1,0]
	s_mov_b32 s100, 0
.Ldfp_noapply_13:
	s_waitcnt lgkmcnt(0)
	s_barrier
	s_add_i32 s27, s27, 1
	s_bitcmp1_b32 s27, 0
	s_cselect_b32 s14, 0x5000, 0
	v_add_u32_e32 v250, s14, v201
	ds_read_b64_tr_b16 v[96:97], v250 offset:24576
	ds_read_b64_tr_b16 v[100:101], v250 offset:24640
	ds_read_b64_tr_b16 v[104:105], v250 offset:24704
	ds_read_b64_tr_b16 v[108:109], v250 offset:24768
	ds_read_b64_tr_b16 v[98:99], v250 offset:27136
	ds_read_b64_tr_b16 v[102:103], v250 offset:27200
	ds_read_b64_tr_b16 v[106:107], v250 offset:27264
	ds_read_b64_tr_b16 v[110:111], v250 offset:27328
	ds_read_b64_tr_b16 v[226:227], v250 offset:29696
	ds_read_b64_tr_b16 v[230:231], v250 offset:29760
	ds_read_b64_tr_b16 v[234:235], v250 offset:29824
	ds_read_b64_tr_b16 v[238:239], v250 offset:29888
	ds_read_b64_tr_b16 v[228:229], v250 offset:32256
	ds_read_b64_tr_b16 v[232:233], v250 offset:32320
	ds_read_b64_tr_b16 v[236:237], v250 offset:32384
	ds_read_b64_tr_b16 v[240:241], v250 offset:32448
	s_waitcnt lgkmcnt(8)
	v_mfma_f32_32x32x16_bf16 v[64:79], v[96:99], v[80:83], v[64:79]
	v_mfma_f32_32x32x16_bf16 v[48:63], v[100:103], v[80:83], v[48:63]
	v_mfma_f32_32x32x16_bf16 v[32:47], v[104:107], v[80:83], v[32:47]
	v_mfma_f32_32x32x16_bf16 v[16:31], v[108:111], v[80:83], v[16:31]
	ds_read_b64_tr_b16 v[96:97], v250 offset:34816
	ds_read_b64_tr_b16 v[100:101], v250 offset:34880
	ds_read_b64_tr_b16 v[104:105], v250 offset:34944
	ds_read_b64_tr_b16 v[108:109], v250 offset:35008
	ds_read_b64_tr_b16 v[98:99], v250 offset:37376
	ds_read_b64_tr_b16 v[102:103], v250 offset:37440
	ds_read_b64_tr_b16 v[106:107], v250 offset:37504
	ds_read_b64_tr_b16 v[110:111], v250 offset:37568
	s_waitcnt lgkmcnt(8)
	v_mfma_f32_32x32x16_bf16 v[64:79], v[226:229], v[84:87], v[64:79]
	v_mfma_f32_32x32x16_bf16 v[48:63], v[230:233], v[84:87], v[48:63]
	v_mfma_f32_32x32x16_bf16 v[32:47], v[234:237], v[84:87], v[32:47]
	v_mfma_f32_32x32x16_bf16 v[16:31], v[238:241], v[84:87], v[16:31]
	ds_read_b64_tr_b16 v[226:227], v250 offset:39936
	ds_read_b64_tr_b16 v[230:231], v250 offset:40000
	ds_read_b64_tr_b16 v[234:235], v250 offset:40064
	ds_read_b64_tr_b16 v[238:239], v250 offset:40128
	ds_read_b64_tr_b16 v[228:229], v250 offset:42496
	ds_read_b64_tr_b16 v[232:233], v250 offset:42560
	ds_read_b64_tr_b16 v[236:237], v250 offset:42624
	ds_read_b64_tr_b16 v[240:241], v250 offset:42688
	s_waitcnt lgkmcnt(8)
	v_mfma_f32_32x32x16_bf16 v[64:79], v[96:99], v[88:91], v[64:79]
	v_mfma_f32_32x32x16_bf16 v[48:63], v[100:103], v[88:91], v[48:63]
	v_mfma_f32_32x32x16_bf16 v[32:47], v[104:107], v[88:91], v[32:47]
	v_mfma_f32_32x32x16_bf16 v[16:31], v[108:111], v[88:91], v[16:31]
	s_waitcnt lgkmcnt(0)
	v_mfma_f32_32x32x16_bf16 v[64:79], v[226:229], v[92:95], v[64:79]
	v_mfma_f32_32x32x16_bf16 v[48:63], v[230:233], v[92:95], v[48:63]
	v_mfma_f32_32x32x16_bf16 v[32:47], v[234:237], v[92:95], v[32:47]
	v_mfma_f32_32x32x16_bf16 v[16:31], v[238:241], v[92:95], v[16:31]
	s_waitcnt lgkmcnt(0)
	s_barrier
	s_nop 7
	s_nop 7
	v_mov_b32_e32 v1, v187
	v_mov_b32_e32 v2, v0
	s_nop 0
	v_mbcnt_lo_u32_b32 v2, -1, v2
	v_mbcnt_hi_u32_b32 v2, -1, v2
	v_lshlrev_b32_e32 v2, 2, v2
	v_xor_b32_e32 v2, 0x80, v2
	ds_bpermute_b32 v2, v2, v1
	s_waitcnt lgkmcnt(0)
	v_add_f32_e32 v1, v1, v2
	v_div_scale_f32 v2, s[4:5], v1, v1, 1.0
	v_rcp_f32_e32 v3, v2
	s_nop 0
	v_fma_f32 v4, -v2, v3, 1.0
	v_fmac_f32_e32 v3, v4, v3
	v_div_scale_f32 v4, vcc, 1.0, v1, 1.0
	v_mul_f32_e32 v5, v4, v3
	v_fma_f32 v6, -v2, v5, v4
	v_fmac_f32_e32 v5, v6, v3
	v_fma_f32 v2, -v2, v5, v4
	v_div_fmas_f32 v2, v2, v3, v5
	v_div_fixup_f32 v6, v2, v1, 1.0
	v_cndmask_b32_e64 v1, 0, 1, s[0:1]
	v_cmp_ne_u32_e64 s[4:5], 1, v1
	s_andn2_b64 vcc, exec, s[0:1]
	s_mov_b64 s[0:1], -1
	s_cbranch_vccnz .LBB0_784
	global_load_dwordx4 v[2:5], v[164:165], off
	global_load_dwordx4 v[8:11], v[164:165], off offset:32
	v_mul_f32_e32 v1, v64, v6
	s_mov_b32 s0, 0x800000
	s_lshl_b64 s[14:15], s[8:9], 2
	v_lshlrev_b32_e32 v139, 2, v162
	s_waitcnt vmcnt(1)
	v_fma_f32 v1, -v160, v1, v2
	v_mul_f32_e32 v2, v65, v6
	v_fma_f32 v7, -v160, v2, v3
	v_mul_f32_e32 v3, v66, v6
	v_fma_f32 v86, -v160, v3, v4
	v_mul_f32_e32 v3, v67, v6
	v_fma_f32 v87, -v160, v3, v5
	v_mul_f32_e32 v3, v68, v6
	s_waitcnt vmcnt(0)
	v_fma_f32 v88, -v160, v3, v8
	v_mul_f32_e32 v3, v69, v6
	v_fma_f32 v89, -v160, v3, v9
	v_mul_f32_e32 v3, v70, v6
	v_fma_f32 v90, -v160, v3, v10
	v_mul_f32_e32 v3, v71, v6
	v_fma_f32 v91, -v160, v3, v11
	global_load_dwordx4 v[8:11], v[164:165], off offset:64
	v_mul_f32_e32 v3, v72, v6
	v_mul_f32_e32 v2, v7, v7
	v_fmac_f32_e32 v2, v1, v1
	v_fmac_f32_e32 v2, v86, v86
	v_fmac_f32_e32 v2, v87, v87
	v_fmac_f32_e32 v2, v88, v88
	v_fmac_f32_e32 v2, v89, v89
	v_fmac_f32_e32 v2, v90, v90
	v_fmac_f32_e32 v2, v91, v91
	v_pk_mul_f32 v[4:5], v[22:23], v[6:7] op_sel_hi:[1,0]
	s_waitcnt vmcnt(0)
	v_fma_f32 v95, -v160, v3, v8
	v_mul_f32_e32 v3, v73, v6
	v_fma_f32 v94, -v160, v3, v9
	v_mul_f32_e32 v3, v74, v6
	v_fma_f32 v93, -v160, v3, v10
	v_mul_f32_e32 v3, v75, v6
	v_fma_f32 v92, -v160, v3, v11
	global_load_dwordx4 v[8:11], v[164:165], off offset:96
	v_mul_f32_e32 v3, v76, v6
	v_fmac_f32_e32 v2, v95, v95
	v_fmac_f32_e32 v2, v94, v94
	v_fmac_f32_e32 v2, v93, v93
	v_fmac_f32_e32 v2, v92, v92
	s_waitcnt vmcnt(0)
	v_fma_f32 v99, -v160, v3, v8
	v_mul_f32_e32 v3, v77, v6
	v_fma_f32 v98, -v160, v3, v9
	v_mul_f32_e32 v3, v78, v6
	v_fma_f32 v97, -v160, v3, v10
	v_mul_f32_e32 v3, v79, v6
	v_fma_f32 v96, -v160, v3, v11
	global_load_dwordx4 v[8:11], v[164:165], off offset:128
	v_mul_f32_e32 v3, v48, v6
	v_fmac_f32_e32 v2, v99, v99
	v_fmac_f32_e32 v2, v98, v98
	v_fmac_f32_e32 v2, v97, v97
	v_fmac_f32_e32 v2, v96, v96
	s_waitcnt vmcnt(0)
	v_fma_f32 v103, -v160, v3, v8
	v_mul_f32_e32 v3, v49, v6
	v_fma_f32 v102, -v160, v3, v9
	v_mul_f32_e32 v3, v50, v6
	v_fma_f32 v101, -v160, v3, v10
	v_mul_f32_e32 v3, v51, v6
	v_fma_f32 v100, -v160, v3, v11
	global_load_dwordx4 v[8:11], v[164:165], off offset:160
	v_mul_f32_e32 v3, v52, v6
	v_fmac_f32_e32 v2, v103, v103
	v_fmac_f32_e32 v2, v102, v102
	v_fmac_f32_e32 v2, v101, v101
	v_fmac_f32_e32 v2, v100, v100
	s_waitcnt vmcnt(0)
	v_fma_f32 v107, -v160, v3, v8
	v_mul_f32_e32 v3, v53, v6
	v_fma_f32 v106, -v160, v3, v9
	v_mul_f32_e32 v3, v54, v6
	v_fma_f32 v105, -v160, v3, v10
	v_mul_f32_e32 v3, v55, v6
	v_fma_f32 v104, -v160, v3, v11
	global_load_dwordx4 v[8:11], v[164:165], off offset:192
	v_mul_f32_e32 v3, v56, v6
	v_fmac_f32_e32 v2, v107, v107
	v_fmac_f32_e32 v2, v106, v106
	v_fmac_f32_e32 v2, v105, v105
	v_fmac_f32_e32 v2, v104, v104
	s_waitcnt vmcnt(0)
	v_fma_f32 v111, -v160, v3, v8
	v_mul_f32_e32 v3, v57, v6
	v_fma_f32 v110, -v160, v3, v9
	v_mul_f32_e32 v3, v58, v6
	v_fma_f32 v109, -v160, v3, v10
	v_mul_f32_e32 v3, v59, v6
	v_fma_f32 v108, -v160, v3, v11
	global_load_dwordx4 v[8:11], v[164:165], off offset:224
	v_mul_f32_e32 v3, v60, v6
	v_fmac_f32_e32 v2, v111, v111
	v_fmac_f32_e32 v2, v110, v110
	v_fmac_f32_e32 v2, v109, v109
	v_fmac_f32_e32 v2, v108, v108
	s_waitcnt vmcnt(0)
	v_fma_f32 v115, -v160, v3, v8
	v_mul_f32_e32 v3, v61, v6
	v_fma_f32 v114, -v160, v3, v9
	v_mul_f32_e32 v3, v62, v6
	v_fma_f32 v113, -v160, v3, v10
	v_mul_f32_e32 v3, v63, v6
	v_fma_f32 v112, -v160, v3, v11
	global_load_dwordx4 v[8:11], v[164:165], off offset:256
	v_mul_f32_e32 v3, v32, v6
	v_fmac_f32_e32 v2, v115, v115
	v_fmac_f32_e32 v2, v114, v114
	v_fmac_f32_e32 v2, v113, v113
	v_fmac_f32_e32 v2, v112, v112
	s_waitcnt vmcnt(0)
	v_fma_f32 v119, -v160, v3, v8
	v_mul_f32_e32 v3, v33, v6
	v_fma_f32 v121, -v160, v3, v9
	v_mul_f32_e32 v3, v34, v6
	v_fma_f32 v118, -v160, v3, v10
	v_mul_f32_e32 v3, v35, v6
	v_fma_f32 v116, -v160, v3, v11
	global_load_dwordx4 v[8:11], v[164:165], off offset:288
	v_mul_f32_e32 v3, v36, v6
	v_fmac_f32_e32 v2, v119, v119
	v_fmac_f32_e32 v2, v121, v121
	v_fmac_f32_e32 v2, v118, v118
	v_fmac_f32_e32 v2, v116, v116
	s_waitcnt vmcnt(0)
	v_fma_f32 v123, -v160, v3, v8
	v_mul_f32_e32 v3, v37, v6
	v_fma_f32 v122, -v160, v3, v9
	v_mul_f32_e32 v3, v38, v6
	v_fma_f32 v120, -v160, v3, v10
	v_mul_f32_e32 v3, v39, v6
	v_fma_f32 v117, -v160, v3, v11
	global_load_dwordx4 v[8:11], v[164:165], off offset:320
	v_mul_f32_e32 v3, v40, v6
	v_fmac_f32_e32 v2, v123, v123
	v_fmac_f32_e32 v2, v122, v122
	v_fmac_f32_e32 v2, v120, v120
	v_fmac_f32_e32 v2, v117, v117
	s_waitcnt vmcnt(0)
	v_fma_f32 v127, -v160, v3, v8
	v_mul_f32_e32 v3, v41, v6
	v_fma_f32 v126, -v160, v3, v9
	v_mul_f32_e32 v3, v42, v6
	v_fma_f32 v125, -v160, v3, v10
	v_mul_f32_e32 v3, v43, v6
	v_fma_f32 v124, -v160, v3, v11
	global_load_dwordx4 v[8:11], v[164:165], off offset:352
	v_mul_f32_e32 v3, v44, v6
	v_fmac_f32_e32 v2, v127, v127
	v_fmac_f32_e32 v2, v126, v126
	v_fmac_f32_e32 v2, v125, v125
	v_fmac_f32_e32 v2, v124, v124
	s_waitcnt vmcnt(0)
	v_fma_f32 v131, -v160, v3, v8
	v_mul_f32_e32 v3, v45, v6
	v_fma_f32 v130, -v160, v3, v9
	v_mul_f32_e32 v3, v46, v6
	v_fma_f32 v129, -v160, v3, v10
	v_mul_f32_e32 v3, v47, v6
	v_fma_f32 v128, -v160, v3, v11
	global_load_dwordx4 v[8:11], v[164:165], off offset:384
	v_mul_f32_e32 v3, v16, v6
	v_fmac_f32_e32 v2, v131, v131
	v_fmac_f32_e32 v2, v130, v130
	v_fmac_f32_e32 v2, v129, v129
	v_fmac_f32_e32 v2, v128, v128
	s_waitcnt vmcnt(0)
	v_fma_f32 v135, -v160, v3, v8
	v_mul_f32_e32 v3, v17, v6
	v_fma_f32 v134, -v160, v3, v9
	v_mul_f32_e32 v3, v18, v6
	v_fma_f32 v133, -v160, v3, v10
	v_mul_f32_e32 v3, v19, v6
	v_fma_f32 v132, -v160, v3, v11
	global_load_dwordx4 v[8:11], v[164:165], off offset:416
	v_fmac_f32_e32 v2, v135, v135
	v_fmac_f32_e32 v2, v134, v134
	v_fmac_f32_e32 v2, v133, v133
	v_mul_f32_e32 v3, v20, v6
	v_fmac_f32_e32 v2, v132, v132
	s_waitcnt vmcnt(0)
	v_fma_f32 v137, -v160, v3, v8
	v_mul_f32_e32 v3, v21, v6
	v_fmac_f32_e32 v2, v137, v137
	v_fma_f32 v136, -v160, v3, v9
	v_pk_fma_f32 v[8:9], v[160:161], v[4:5], v[10:11] neg_lo:[1,0,0] neg_hi:[1,0,0]
	v_fmac_f32_e32 v2, v136, v136
	v_pk_mul_f32 v[4:5], v[8:9], v[8:9]
	v_pk_mul_f32 v[10:11], v[24:25], v[6:7] op_sel_hi:[1,0]
	v_add_f32_e32 v2, v4, v2
	v_add_f32_e32 v14, v5, v2
	global_load_dwordx4 v[2:5], v[164:165], off offset:448
	s_waitcnt vmcnt(0)
	v_pk_fma_f32 v[12:13], v[160:161], v[10:11], v[2:3] neg_lo:[1,0,0] neg_hi:[1,0,0]
	s_nop 0
	v_pk_mul_f32 v[2:3], v[12:13], v[12:13]
	s_nop 0
	v_add_f32_e32 v2, v2, v14
	v_add_f32_e32 v14, v3, v2
	v_pk_mul_f32 v[2:3], v[26:27], v[6:7] op_sel_hi:[1,0]
	s_nop 0
	v_pk_fma_f32 v[10:11], v[160:161], v[2:3], v[4:5] neg_lo:[1,0,0] neg_hi:[1,0,0]
	s_nop 0
	v_pk_mul_f32 v[2:3], v[10:11], v[10:11]
	s_nop 0
	v_add_f32_e32 v2, v2, v14
	v_add_f32_e32 v82, v3, v2
	global_load_dwordx4 v[2:5], v[164:165], off offset:480
	v_pk_mul_f32 v[14:15], v[28:29], v[6:7] op_sel_hi:[1,0]
	s_waitcnt vmcnt(0)
	v_pk_fma_f32 v[80:81], v[160:161], v[14:15], v[2:3] neg_lo:[1,0,0] neg_hi:[1,0,0]
	s_nop 0
	v_pk_mul_f32 v[2:3], v[80:81], v[80:81]
	s_nop 0
	v_add_f32_e32 v2, v2, v82
	v_add_f32_e32 v82, v3, v2
	v_pk_mul_f32 v[2:3], v[30:31], v[6:7] op_sel_hi:[1,0]
	s_nop 0
	v_pk_fma_f32 v[14:15], v[160:161], v[2:3], v[4:5] neg_lo:[1,0,0] neg_hi:[1,0,0]
	v_lshlrev_b32_e32 v4, 1, v162
	v_pk_mul_f32 v[2:3], v[14:15], v[14:15]
	v_mov_b32_e32 v5, v0
	v_add_f32_e32 v2, v2, v82
	v_add_f32_e32 v2, v3, v2
	v_mov_b32_e32 v3, v0
	s_nop 0
	v_mbcnt_lo_u32_b32 v3, -1, v3
	v_mbcnt_hi_u32_b32 v3, -1, v3
	v_lshlrev_b32_e32 v3, 2, v3
	v_xor_b32_e32 v3, 0x80, v3
	ds_bpermute_b32 v3, v3, v2
	s_waitcnt lgkmcnt(0)
	v_add_f32_e32 v2, v2, v3
	v_fmamk_f32 v2, v2, 0x3c000000, v217
	v_cmp_gt_f32_e32 vcc, s0, v2
	v_mul_f32_e32 v3, 0x4b800000, v2
	s_mov_b64 s[0:1], s[56:57]
	v_cndmask_b32_e32 v2, v2, v3, vcc
	v_rsq_f32_e32 v2, v2
	s_load_dwordx2 s[0:1], s[0:1], 0xf0
	v_mul_f32_e32 v3, 0x45800000, v2
	v_cndmask_b32_e32 v2, v2, v3, vcc
	v_mul_f32_e32 v138, v163, v2
	s_waitcnt lgkmcnt(0)
	v_lshl_add_u64 v[2:3], s[0:1], 0, v[178:179]
	v_lshl_add_u64 v[2:3], v[2:3], 0, s[36:37]
	v_lshl_add_u64 v[84:85], v[2:3], 0, v[4:5]
	s_mov_b64 s[0:1], 0x6a701000
	v_lshl_add_u64 v[82:83], v[84:85], 0, s[0:1]
	s_mov_b64 s[0:1], s[56:57]
	s_load_dwordx2 s[0:1], s[0:1], 0x88
	v_mul_f32_e32 v1, v1, v138
	s_waitcnt lgkmcnt(0)
	s_add_u32 s0, s0, s14
	s_addc_u32 s1, s1, s15
	global_load_dwordx4 v[2:5], v139, s[0:1]
	s_waitcnt vmcnt(0)
	v_mul_f32_e32 v1, v2, v1
	v_mul_f32_e32 v2, v7, v138
	v_mul_f32_e32 v2, v3, v2
	v_cvt_pk_bf16_f32 v2, v1, v2
	v_mul_f32_e32 v1, v86, v138
	v_mul_f32_e32 v1, v4, v1
	v_mul_f32_e32 v3, v87, v138
	v_add_co_u32_e32 v4, vcc, s42, v84
	v_mul_f32_e32 v3, v5, v3
	s_nop 0
	v_addc_co_u32_e32 v5, vcc, 0, v85, vcc
	v_cvt_pk_bf16_f32 v3, v1, v3
	global_store_dwordx2 v[4:5], v[2:3], off
	global_load_dwordx4 v[2:5], v139, s[0:1] offset:32
	v_mul_f32_e32 v1, v88, v138
	s_waitcnt vmcnt(0)
	v_mul_f32_e32 v1, v2, v1
	v_mul_f32_e32 v2, v89, v138
	v_mul_f32_e32 v2, v3, v2
	v_mul_f32_e32 v3, v91, v138
	v_cvt_pk_bf16_f32 v2, v1, v2
	v_mul_f32_e32 v1, v90, v138
	v_mul_f32_e32 v3, v5, v3
	v_mul_f32_e32 v1, v4, v1
	v_cvt_pk_bf16_f32 v3, v1, v3
	global_store_dwordx2 v[82:83], v[2:3], off offset:16
	global_load_dwordx4 v[2:5], v139, s[0:1] offset:64
	v_mul_f32_e32 v1, v95, v138
	s_waitcnt vmcnt(0)
	v_mul_f32_e32 v1, v2, v1
	v_mul_f32_e32 v2, v94, v138
	v_mul_f32_e32 v2, v3, v2
	v_mul_f32_e32 v3, v92, v138
	v_cvt_pk_bf16_f32 v2, v1, v2
	v_mul_f32_e32 v1, v93, v138
	v_mul_f32_e32 v3, v5, v3
	v_mul_f32_e32 v1, v4, v1
	v_cvt_pk_bf16_f32 v3, v1, v3
	global_store_dwordx2 v[82:83], v[2:3], off offset:32
	global_load_dwordx4 v[2:5], v139, s[0:1] offset:96
	v_mul_f32_e32 v1, v99, v138
	s_waitcnt vmcnt(0)
	v_mul_f32_e32 v1, v2, v1
	v_mul_f32_e32 v2, v98, v138
	v_mul_f32_e32 v2, v3, v2
	v_mul_f32_e32 v3, v96, v138
	v_cvt_pk_bf16_f32 v2, v1, v2
	v_mul_f32_e32 v1, v97, v138
	v_mul_f32_e32 v3, v5, v3
	v_mul_f32_e32 v1, v4, v1
	v_cvt_pk_bf16_f32 v3, v1, v3
	global_store_dwordx2 v[82:83], v[2:3], off offset:48
	global_load_dwordx4 v[2:5], v139, s[0:1] offset:128
	v_mul_f32_e32 v1, v103, v138
	s_waitcnt vmcnt(0)
	v_mul_f32_e32 v1, v2, v1
	v_mul_f32_e32 v2, v102, v138
	v_mul_f32_e32 v2, v3, v2
	v_mul_f32_e32 v3, v100, v138
	v_cvt_pk_bf16_f32 v2, v1, v2
	v_mul_f32_e32 v1, v101, v138
	v_mul_f32_e32 v3, v5, v3
	v_mul_f32_e32 v1, v4, v1
	v_cvt_pk_bf16_f32 v3, v1, v3
	global_store_dwordx2 v[82:83], v[2:3], off offset:64
	global_load_dwordx4 v[2:5], v139, s[0:1] offset:160
	v_mul_f32_e32 v1, v107, v138
	s_waitcnt vmcnt(0)
	v_mul_f32_e32 v1, v2, v1
	v_mul_f32_e32 v2, v106, v138
	v_mul_f32_e32 v2, v3, v2
	v_mul_f32_e32 v3, v104, v138
	v_cvt_pk_bf16_f32 v2, v1, v2
	v_mul_f32_e32 v1, v105, v138
	v_mul_f32_e32 v3, v5, v3
	v_mul_f32_e32 v1, v4, v1
	v_cvt_pk_bf16_f32 v3, v1, v3
	global_store_dwordx2 v[82:83], v[2:3], off offset:80
	global_load_dwordx4 v[2:5], v139, s[0:1] offset:192
	v_mul_f32_e32 v1, v111, v138
	s_waitcnt vmcnt(0)
	v_mul_f32_e32 v1, v2, v1
	v_mul_f32_e32 v2, v110, v138
	v_mul_f32_e32 v2, v3, v2
	v_mul_f32_e32 v3, v108, v138
	v_cvt_pk_bf16_f32 v2, v1, v2
	v_mul_f32_e32 v1, v109, v138
	v_mul_f32_e32 v3, v5, v3
	v_mul_f32_e32 v1, v4, v1
	v_cvt_pk_bf16_f32 v3, v1, v3
	global_store_dwordx2 v[82:83], v[2:3], off offset:96
	global_load_dwordx4 v[2:5], v139, s[0:1] offset:224
	v_mul_f32_e32 v1, v115, v138
	s_waitcnt vmcnt(0)
	v_mul_f32_e32 v1, v2, v1
	v_mul_f32_e32 v2, v114, v138
	v_mul_f32_e32 v2, v3, v2
	v_mul_f32_e32 v3, v112, v138
	v_cvt_pk_bf16_f32 v2, v1, v2
	v_mul_f32_e32 v1, v113, v138
	v_mul_f32_e32 v3, v5, v3
	v_mul_f32_e32 v1, v4, v1
	v_cvt_pk_bf16_f32 v3, v1, v3
	global_store_dwordx2 v[82:83], v[2:3], off offset:112
	global_load_dwordx4 v[2:5], v139, s[0:1] offset:256
	v_mul_f32_e32 v1, v119, v138
	s_waitcnt vmcnt(0)
	v_mul_f32_e32 v1, v2, v1
	v_mul_f32_e32 v2, v121, v138
	v_mul_f32_e32 v2, v3, v2
	v_mul_f32_e32 v3, v116, v138
	v_cvt_pk_bf16_f32 v2, v1, v2
	v_mul_f32_e32 v1, v118, v138
	v_mul_f32_e32 v3, v5, v3
	v_mul_f32_e32 v1, v4, v1
	v_cvt_pk_bf16_f32 v3, v1, v3
	global_store_dwordx2 v[82:83], v[2:3], off offset:128
	global_load_dwordx4 v[2:5], v139, s[0:1] offset:288
	v_mul_f32_e32 v1, v123, v138
	s_waitcnt vmcnt(0)
	v_mul_f32_e32 v1, v2, v1
	v_mul_f32_e32 v2, v122, v138
	v_mul_f32_e32 v2, v3, v2
	v_mul_f32_e32 v3, v117, v138
	v_cvt_pk_bf16_f32 v2, v1, v2
	v_mul_f32_e32 v1, v120, v138
	v_mul_f32_e32 v3, v5, v3
	v_mul_f32_e32 v1, v4, v1
	v_cvt_pk_bf16_f32 v3, v1, v3
	global_store_dwordx2 v[82:83], v[2:3], off offset:144
	global_load_dwordx4 v[2:5], v139, s[0:1] offset:320
	v_mul_f32_e32 v1, v127, v138
	s_waitcnt vmcnt(0)
	v_mul_f32_e32 v1, v2, v1
	v_mul_f32_e32 v2, v126, v138
	v_mul_f32_e32 v2, v3, v2
	v_mul_f32_e32 v3, v124, v138
	v_cvt_pk_bf16_f32 v2, v1, v2
	v_mul_f32_e32 v1, v125, v138
	v_mul_f32_e32 v3, v5, v3
	v_mul_f32_e32 v1, v4, v1
	v_cvt_pk_bf16_f32 v3, v1, v3
	global_store_dwordx2 v[82:83], v[2:3], off offset:160
	global_load_dwordx4 v[2:5], v139, s[0:1] offset:352
	v_mul_f32_e32 v1, v131, v138
	s_waitcnt vmcnt(0)
	v_mul_f32_e32 v1, v2, v1
	v_mul_f32_e32 v2, v130, v138
	v_mul_f32_e32 v2, v3, v2
	v_mul_f32_e32 v3, v128, v138
	v_cvt_pk_bf16_f32 v2, v1, v2
	v_mul_f32_e32 v1, v129, v138
	v_mul_f32_e32 v3, v5, v3
	v_mul_f32_e32 v1, v4, v1
	v_cvt_pk_bf16_f32 v3, v1, v3
	global_store_dwordx2 v[82:83], v[2:3], off offset:176
	global_load_dwordx4 v[2:5], v139, s[0:1] offset:384
	v_mul_f32_e32 v1, v135, v138
	s_waitcnt vmcnt(0)
	v_mul_f32_e32 v1, v2, v1
	v_mul_f32_e32 v2, v134, v138
	v_mul_f32_e32 v2, v3, v2
	v_mul_f32_e32 v3, v132, v138
	v_cvt_pk_bf16_f32 v2, v1, v2
	v_mul_f32_e32 v1, v133, v138
	v_mul_f32_e32 v3, v5, v3
	v_mul_f32_e32 v1, v4, v1
	v_cvt_pk_bf16_f32 v3, v1, v3
	global_store_dwordx2 v[82:83], v[2:3], off offset:192
	global_load_dwordx4 v[2:5], v139, s[0:1] offset:416
	v_mul_f32_e32 v1, v137, v138
	s_waitcnt vmcnt(0)
	v_mul_f32_e32 v1, v1, v2
	v_mul_f32_e32 v2, v136, v138
	v_mul_f32_e32 v2, v2, v3
	v_mul_f32_e32 v3, v9, v138
	v_cvt_pk_bf16_f32 v2, v1, v2
	v_mul_f32_e32 v1, v8, v138
	v_mul_f32_e32 v3, v3, v5
	v_mul_f32_e32 v1, v1, v4
	v_cvt_pk_bf16_f32 v3, v1, v3
	global_store_dwordx2 v[82:83], v[2:3], off offset:208
	global_load_dwordx4 v[2:5], v139, s[0:1] offset:448
	v_mul_f32_e32 v1, v12, v138
	s_waitcnt vmcnt(0)
	v_mul_f32_e32 v1, v1, v2
	v_mul_f32_e32 v2, v13, v138
	v_mul_f32_e32 v2, v2, v3
	v_mul_f32_e32 v3, v11, v138
	v_cvt_pk_bf16_f32 v2, v1, v2
	v_mul_f32_e32 v1, v10, v138
	v_mul_f32_e32 v3, v3, v5
	v_mul_f32_e32 v1, v1, v4
	v_cvt_pk_bf16_f32 v3, v1, v3
	global_store_dwordx2 v[82:83], v[2:3], off offset:224
	global_load_dwordx4 v[2:5], v139, s[0:1] offset:480
	v_mul_f32_e32 v1, v80, v138
	s_waitcnt vmcnt(0)
	v_mul_f32_e32 v1, v1, v2
	v_mul_f32_e32 v2, v81, v138
	v_mul_f32_e32 v2, v2, v3
	v_mul_f32_e32 v3, v15, v138
	v_cvt_pk_bf16_f32 v2, v1, v2
	v_mul_f32_e32 v1, v14, v138
	v_mul_f32_e32 v3, v3, v5
	v_mul_f32_e32 v1, v1, v4
	v_cvt_pk_bf16_f32 v3, v1, v3
	global_store_dwordx2 v[82:83], v[2:3], off offset:240
	s_cbranch_execnz .LBB0_754
	s_branch .LBB0_785
